# phase_up epilogue (waits to first consumer, guide 7.2): each block's LDS read-back wait and 16-byte stores deferred to just before the next block's first LDS write
# speedup vs baseline: 1.0133x; 1.0133x over previous
.LBB0_915:
	s_or_b64 exec, exec, s[0:1]
	v_lshl_add_u64 v[0:1], s[26:27], 0, v[24:25]
	v_add_u32_e32 v24, v148, v121
	v_ashrrev_i32_e32 v25, 31, v24
	v_lshlrev_b64 v[22:23], v22, v[24:25]
	v_mov_b32_e32 v39, v4
	v_lshl_add_u64 v[22:23], v[22:23], 0, v[38:39]
	v_mad_u64_u32 v[0:1], s[0:1], v22, s50, v[0:1]
	v_mad_i32_i24 v1, v23, s50, v1
	v_lshl_add_u64 v[0:1], v[118:119], 1, v[0:1]
	v_mov_b32_e32 v3, v4
	v_lshl_add_u64 v[0:1], v[0:1], 0, v[2:3]
	v_pk_mul_f32 v[2:3], v[6:7], s[64:65] op_sel_hi:[1,0]
	v_pk_mul_f32 v[6:7], v[8:9], s[64:65] op_sel_hi:[1,0]
	v_cvt_pk_bf16_f32 v2, v2, v3
	v_cvt_pk_bf16_f32 v3, v6, v7
	s_waitcnt lgkmcnt(0)
	global_store_dwordx4 v184, v[186:189], s[70:71]
	global_store_dwordx4 v184, v[190:193], s[70:71] offset:3072
	s_nop 0
	v_readfirstlane_b32 s70, v0
	v_readfirstlane_b32 s71, v1
	ds_write_b64 v182, v[2:3]
	v_pk_mul_f32 v[2:3], v[10:11], s[64:65] op_sel_hi:[1,0]
	v_pk_mul_f32 v[6:7], v[12:13], s[64:65] op_sel_hi:[1,0]
	v_cvt_pk_bf16_f32 v2, v2, v3
	v_cvt_pk_bf16_f32 v3, v6, v7
	ds_write_b64 v182, v[2:3] offset:16
	v_pk_mul_f32 v[2:3], v[14:15], s[64:65] op_sel_hi:[1,0]
	v_pk_mul_f32 v[6:7], v[16:17], s[64:65] op_sel_hi:[1,0]
	v_cvt_pk_bf16_f32 v2, v2, v3
	v_cvt_pk_bf16_f32 v3, v6, v7
	ds_write_b64 v182, v[2:3] offset:32
	v_pk_mul_f32 v[2:3], v[18:19], s[64:65] op_sel_hi:[1,0]
	v_pk_mul_f32 v[6:7], v[20:21], s[64:65] op_sel_hi:[1,0]
	v_cvt_pk_bf16_f32 v2, v2, v3
	v_cvt_pk_bf16_f32 v3, v6, v7
	ds_write_b64 v182, v[2:3] offset:48
	ds_read_b128 v[186:189], v183
	ds_read_b128 v[190:193], v183 offset:1280
	s_waitcnt lgkmcnt(1)
	global_store_dwordx4 v184, v[186:189], s[70:71]
	s_waitcnt lgkmcnt(0)
	global_store_dwordx4 v184, v[190:193], s[70:71] offset:3072

.LBB0_922:
	s_or_saveexec_b64 s[0:1], s[0:1]
	v_lshlrev_b32_e32 v0, 1, v151
	s_xor_b64 exec, exec, s[0:1]
	s_cbranch_execz .LBB0_924
	v_lshl_add_u64 v[134:135], s[26:27], 0, v[134:135]
	v_lshlrev_b32_e32 v1, 7, v2
	v_mad_i64_i32 v[2:3], s[14:15], v1, v3, v[134:135]
	v_lshlrev_b32_e32 v134, 7, v152
	v_mov_b32_e32 v135, v4
	v_lshl_add_u64 v[2:3], v[2:3], 0, v[134:135]
	v_mov_b32_e32 v1, v4
	v_lshl_add_u64 v[2:3], v[2:3], 0, v[0:1]
	v_cvt_pk_bf16_f32 v118, v118, v119
	v_cvt_pk_bf16_f32 v119, v120, v121
	s_nop 0
	v_readfirstlane_b32 s70, v2
	v_readfirstlane_b32 s71, v3
	ds_write_b64 v182, v[118:119]
	v_cvt_pk_bf16_f32 v118, v122, v123
	v_cvt_pk_bf16_f32 v119, v124, v125
	ds_write_b64 v182, v[118:119] offset:16
	v_cvt_pk_bf16_f32 v118, v126, v127
	v_cvt_pk_bf16_f32 v119, v128, v129
	ds_write_b64 v182, v[118:119] offset:32
	v_cvt_pk_bf16_f32 v118, v130, v131
	v_cvt_pk_bf16_f32 v119, v132, v133
	ds_write_b64 v182, v[118:119] offset:48
	ds_read_b128 v[186:189], v183
	ds_read_b128 v[190:193], v183 offset:1280
.LBB0_924:
	s_or_b64 exec, exec, s[0:1]
	v_mov_b64_e32 v[2:3], 0x100
	v_mov_b64_e32 v[118:119], 0xc952000
	v_mov_b64_e32 v[120:121], 0xdb62000
	v_mov_b32_e32 v1, v136
	s_and_saveexec_b64 s[0:1], s[6:7]
	v_mov_b64_e32 v[2:3], 0x1200
	v_mov_b64_e32 v[118:119], 0xd152000
	v_mov_b64_e32 v[120:121], 0xe362000
	v_mov_b32_e32 v146, v147
	v_mov_b32_e32 v1, v148
	s_or_b64 exec, exec, s[0:1]
	v_or_b32_e32 v3, 32, v150
	v_lshl_or_b32 v1, v1, 3, v137
	v_add_u32_e32 v122, v149, v3
	s_and_saveexec_b64 s[0:1], vcc
	s_xor_b64 s[0:1], exec, s[0:1]
	s_cbranch_execz .LBB0_928
	v_lshl_add_u64 v[118:119], s[26:27], 0, v[120:121]
	v_mad_i64_i32 v[120:121], s[6:7], v2, v1, 0
	v_lshlrev_b64 v[120:121], 7, v[120:121]
	v_lshl_add_u64 v[118:119], v[118:119], 0, v[120:121]
	v_mad_u64_u32 v[120:121], s[6:7], v2, v122, 0
	v_lshl_add_u64 v[118:119], v[120:121], 1, v[118:119]
	v_lshlrev_b32_e32 v120, 1, v146
	v_mov_b32_e32 v121, v4
	v_lshl_add_u64 v[118:119], v[118:119], 0, v[120:121]
	v_cvt_pk_bf16_f32 v1, v102, s0
	global_store_short v[118:119], v1, off
	v_cvt_pk_bf16_f32 v1, v103, s0
	v_lshlrev_b32_e32 v102, 1, v2
	v_mov_b32_e32 v103, v4
	v_lshl_add_u64 v[118:119], v[118:119], 0, v[102:103]
	global_store_short v[118:119], v1, off
	v_cvt_pk_bf16_f32 v1, v104, s0
	v_lshl_add_u64 v[118:119], v[118:119], 0, v[102:103]
	global_store_short v[118:119], v1, off
	v_cvt_pk_bf16_f32 v1, v105, s0
	v_lshl_add_u64 v[104:105], v[118:119], 0, v[102:103]
	global_store_short v[104:105], v1, off
	v_cvt_pk_bf16_f32 v1, v106, s0
	v_mad_u64_u32 v[104:105], s[6:7], v2, 10, v[104:105]
	global_store_short v[104:105], v1, off
	v_cvt_pk_bf16_f32 v1, v107, s0
	v_lshl_add_u64 v[104:105], v[104:105], 0, v[102:103]
	global_store_short v[104:105], v1, off
	v_cvt_pk_bf16_f32 v1, v108, s0
	v_lshl_add_u64 v[104:105], v[104:105], 0, v[102:103]
	global_store_short v[104:105], v1, off
	v_cvt_pk_bf16_f32 v1, v109, s0
	v_lshl_add_u64 v[104:105], v[104:105], 0, v[102:103]
	global_store_short v[104:105], v1, off
	v_cvt_pk_bf16_f32 v1, v110, s0
	v_mad_u64_u32 v[104:105], s[6:7], v2, 10, v[104:105]
	global_store_short v[104:105], v1, off
	v_cvt_pk_bf16_f32 v1, v111, s0
	v_lshl_add_u64 v[104:105], v[104:105], 0, v[102:103]
	global_store_short v[104:105], v1, off
	v_cvt_pk_bf16_f32 v1, v112, s0
	v_lshl_add_u64 v[104:105], v[104:105], 0, v[102:103]
	global_store_short v[104:105], v1, off
	v_cvt_pk_bf16_f32 v1, v113, s0
	v_lshl_add_u64 v[104:105], v[104:105], 0, v[102:103]
	global_store_short v[104:105], v1, off
	v_cvt_pk_bf16_f32 v1, v114, s0
	v_mad_u64_u32 v[2:3], s[6:7], v2, 10, v[104:105]
	global_store_short v[2:3], v1, off
	v_cvt_pk_bf16_f32 v1, v115, s0
	v_lshl_add_u64 v[2:3], v[2:3], 0, v[102:103]
	global_store_short v[2:3], v1, off
	v_cvt_pk_bf16_f32 v1, v116, s0
	v_lshl_add_u64 v[2:3], v[2:3], 0, v[102:103]
	global_store_short v[2:3], v1, off
	v_cvt_pk_bf16_f32 v1, v117, s0
	v_lshl_add_u64 v[2:3], v[2:3], 0, v[102:103]
	global_store_short v[2:3], v1, off
.LBB0_928:
	s_andn2_saveexec_b64 s[0:1], s[0:1]
	s_cbranch_execz .LBB0_930
	v_lshl_add_u64 v[118:119], s[26:27], 0, v[118:119]
	v_lshlrev_b32_e32 v2, 7, v2
	v_mad_i64_i32 v[2:3], s[6:7], v2, v1, v[118:119]
	v_lshlrev_b32_e32 v118, 7, v146
	v_mov_b32_e32 v119, v4
	v_lshl_add_u64 v[2:3], v[2:3], 0, v[118:119]
	v_mov_b32_e32 v1, v4
	v_lshl_add_u64 v[2:3], v[2:3], 0, v[0:1]
	v_cvt_pk_bf16_f32 v102, v102, v103
	v_cvt_pk_bf16_f32 v103, v104, v105
	s_waitcnt lgkmcnt(0)
	global_store_dwordx4 v185, v[186:189], s[70:71]
	global_store_dwordx4 v185, v[190:193], s[70:71] offset:2048
	s_nop 0
	v_readfirstlane_b32 s70, v2
	v_readfirstlane_b32 s71, v3
	ds_write_b64 v182, v[102:103]
	v_cvt_pk_bf16_f32 v102, v106, v107
	v_cvt_pk_bf16_f32 v103, v108, v109
	ds_write_b64 v182, v[102:103] offset:16
	v_cvt_pk_bf16_f32 v102, v110, v111
	v_cvt_pk_bf16_f32 v103, v112, v113
	ds_write_b64 v182, v[102:103] offset:32
	v_cvt_pk_bf16_f32 v102, v114, v115
	v_cvt_pk_bf16_f32 v103, v116, v117
	ds_write_b64 v182, v[102:103] offset:48
	ds_read_b128 v[186:189], v183
	ds_read_b128 v[190:193], v183 offset:1280

.LBB0_934:
	s_andn2_saveexec_b64 s[6:7], s[6:7]
	s_cbranch_execz .LBB0_936
	v_lshl_add_u64 v[102:103], s[26:27], 0, v[102:103]
	v_lshlrev_b32_e32 v2, 7, v2
	v_mad_i64_i32 v[2:3], s[14:15], v2, v3, v[102:103]
	v_lshlrev_b32_e32 v102, 7, v1
	v_mov_b32_e32 v103, v4
	v_lshl_add_u64 v[2:3], v[2:3], 0, v[102:103]
	v_mov_b32_e32 v1, v4
	v_lshl_add_u64 v[2:3], v[2:3], 0, v[0:1]
	v_cvt_pk_bf16_f32 v86, v86, v87
	v_cvt_pk_bf16_f32 v87, v88, v89
	s_waitcnt lgkmcnt(0)
	global_store_dwordx4 v185, v[186:189], s[70:71] offset:64
	global_store_dwordx4 v185, v[190:193], s[70:71] offset:2112
	s_nop 0
	v_readfirstlane_b32 s70, v2
	v_readfirstlane_b32 s71, v3
	ds_write_b64 v182, v[86:87]
	v_cvt_pk_bf16_f32 v86, v90, v91
	v_cvt_pk_bf16_f32 v87, v92, v93
	ds_write_b64 v182, v[86:87] offset:16
	v_cvt_pk_bf16_f32 v86, v94, v95
	v_cvt_pk_bf16_f32 v87, v96, v97
	ds_write_b64 v182, v[86:87] offset:32
	v_cvt_pk_bf16_f32 v86, v98, v99
	v_cvt_pk_bf16_f32 v87, v100, v101
	ds_write_b64 v182, v[86:87] offset:48
	ds_read_b128 v[186:189], v183
	ds_read_b128 v[190:193], v183 offset:1280

.LBB0_940:
	s_andn2_saveexec_b64 s[0:1], s[0:1]
	s_cbranch_execz .LBB0_942
	v_lshl_add_u64 v[86:87], s[26:27], 0, v[86:87]
	v_lshlrev_b32_e32 v2, 7, v2
	v_mad_i64_i32 v[2:3], s[6:7], v2, v1, v[86:87]
	v_lshlrev_b32_e32 v86, 7, v106
	v_mov_b32_e32 v87, v4
	v_lshl_add_u64 v[2:3], v[2:3], 0, v[86:87]
	v_mov_b32_e32 v1, v4
	v_lshl_add_u64 v[2:3], v[2:3], 0, v[0:1]
	v_cvt_pk_bf16_f32 v70, v70, v71
	v_cvt_pk_bf16_f32 v71, v72, v73
	s_waitcnt lgkmcnt(0)
	global_store_dwordx4 v185, v[186:189], s[70:71]
	global_store_dwordx4 v185, v[190:193], s[70:71] offset:2048
	s_nop 0
	v_readfirstlane_b32 s70, v2
	v_readfirstlane_b32 s71, v3
	ds_write_b64 v182, v[70:71]
	v_cvt_pk_bf16_f32 v70, v74, v75
	v_cvt_pk_bf16_f32 v71, v76, v77
	ds_write_b64 v182, v[70:71] offset:16
	v_cvt_pk_bf16_f32 v70, v78, v79
	v_cvt_pk_bf16_f32 v71, v80, v81
	ds_write_b64 v182, v[70:71] offset:32
	v_cvt_pk_bf16_f32 v70, v82, v83
	v_cvt_pk_bf16_f32 v71, v84, v85
	ds_write_b64 v182, v[70:71] offset:48
	ds_read_b128 v[186:189], v183
	ds_read_b128 v[190:193], v183 offset:1280

.LBB0_946:
	s_andn2_saveexec_b64 s[6:7], s[6:7]
	s_cbranch_execz .LBB0_948
	v_lshl_add_u64 v[70:71], s[26:27], 0, v[70:71]
	v_lshlrev_b32_e32 v2, 7, v2
	v_mad_i64_i32 v[2:3], s[14:15], v2, v3, v[70:71]
	v_lshlrev_b32_e32 v70, 7, v1
	v_mov_b32_e32 v71, v4
	v_lshl_add_u64 v[2:3], v[2:3], 0, v[70:71]
	v_mov_b32_e32 v1, v4
	v_lshl_add_u64 v[2:3], v[2:3], 0, v[0:1]
	v_cvt_pk_bf16_f32 v54, v54, v55
	v_cvt_pk_bf16_f32 v55, v56, v57
	s_waitcnt lgkmcnt(0)
	global_store_dwordx4 v185, v[186:189], s[70:71] offset:64
	global_store_dwordx4 v185, v[190:193], s[70:71] offset:2112
	s_nop 0
	v_readfirstlane_b32 s70, v2
	v_readfirstlane_b32 s71, v3
	ds_write_b64 v182, v[54:55]
	v_cvt_pk_bf16_f32 v54, v58, v59
	v_cvt_pk_bf16_f32 v55, v60, v61
	ds_write_b64 v182, v[54:55] offset:16
	v_cvt_pk_bf16_f32 v54, v62, v63
	v_cvt_pk_bf16_f32 v55, v64, v65
	ds_write_b64 v182, v[54:55] offset:32
	v_cvt_pk_bf16_f32 v54, v66, v67
	v_cvt_pk_bf16_f32 v55, v68, v69
	ds_write_b64 v182, v[54:55] offset:48
	ds_read_b128 v[186:189], v183
	ds_read_b128 v[190:193], v183 offset:1280

.LBB0_952:
	s_andn2_saveexec_b64 s[0:1], s[0:1]
	s_cbranch_execz .LBB0_954
	v_lshl_add_u64 v[54:55], s[26:27], 0, v[54:55]
	v_lshlrev_b32_e32 v2, 7, v2
	v_mad_i64_i32 v[2:3], s[6:7], v2, v1, v[54:55]
	v_lshlrev_b32_e32 v54, 7, v74
	v_mov_b32_e32 v55, v4
	v_lshl_add_u64 v[2:3], v[2:3], 0, v[54:55]
	v_mov_b32_e32 v1, v4
	v_lshl_add_u64 v[2:3], v[2:3], 0, v[0:1]
	v_cvt_pk_bf16_f32 v38, v38, v39
	v_cvt_pk_bf16_f32 v39, v40, v41
	s_waitcnt lgkmcnt(0)
	global_store_dwordx4 v185, v[186:189], s[70:71]
	global_store_dwordx4 v185, v[190:193], s[70:71] offset:2048
	s_nop 0
	v_readfirstlane_b32 s70, v2
	v_readfirstlane_b32 s71, v3
	ds_write_b64 v182, v[38:39]
	v_cvt_pk_bf16_f32 v38, v42, v43
	v_cvt_pk_bf16_f32 v39, v44, v45
	ds_write_b64 v182, v[38:39] offset:16
	v_cvt_pk_bf16_f32 v38, v46, v47
	v_cvt_pk_bf16_f32 v39, v48, v49
	ds_write_b64 v182, v[38:39] offset:32
	v_cvt_pk_bf16_f32 v38, v50, v51
	v_cvt_pk_bf16_f32 v39, v52, v53
	ds_write_b64 v182, v[38:39] offset:48
	ds_read_b128 v[186:189], v183
	ds_read_b128 v[190:193], v183 offset:1280

.LBB0_958:
	s_andn2_saveexec_b64 s[4:5], s[4:5]
	s_cbranch_execz .LBB0_960
	v_lshl_add_u64 v[38:39], s[26:27], 0, v[38:39]
	v_lshlrev_b32_e32 v2, 7, v2
	v_mad_i64_i32 v[2:3], s[6:7], v2, v3, v[38:39]
	v_lshlrev_b32_e32 v38, 7, v1
	v_mov_b32_e32 v39, v4
	v_lshl_add_u64 v[2:3], v[2:3], 0, v[38:39]
	v_mov_b32_e32 v1, v4
	v_lshl_add_u64 v[2:3], v[2:3], 0, v[0:1]
	v_cvt_pk_bf16_f32 v22, v22, v23
	v_cvt_pk_bf16_f32 v23, v24, v25
	s_waitcnt lgkmcnt(0)
	global_store_dwordx4 v185, v[186:189], s[70:71] offset:64
	global_store_dwordx4 v185, v[190:193], s[70:71] offset:2112
	s_nop 0
	v_readfirstlane_b32 s70, v2
	v_readfirstlane_b32 s71, v3
	ds_write_b64 v182, v[22:23]
	v_cvt_pk_bf16_f32 v22, v26, v27
	v_cvt_pk_bf16_f32 v23, v28, v29
	ds_write_b64 v182, v[22:23] offset:16
	v_cvt_pk_bf16_f32 v22, v30, v31
	v_cvt_pk_bf16_f32 v23, v32, v33
	ds_write_b64 v182, v[22:23] offset:32
	v_cvt_pk_bf16_f32 v22, v34, v35
	v_cvt_pk_bf16_f32 v23, v36, v37
	ds_write_b64 v182, v[22:23] offset:48
	ds_read_b128 v[186:189], v183
	ds_read_b128 v[190:193], v183 offset:1280

.LBB0_964:
	s_andn2_saveexec_b64 s[0:1], s[0:1]
	s_cbranch_execz .LBB0_966
	v_lshl_add_u64 v[22:23], s[26:27], 0, v[22:23]
	v_lshlrev_b32_e32 v2, 7, v2
	v_mad_i64_i32 v[2:3], s[4:5], v2, v1, v[22:23]
	v_lshlrev_b32_e32 v22, 7, v42
	v_mov_b32_e32 v23, v4
	v_lshl_add_u64 v[2:3], v[2:3], 0, v[22:23]
	v_mov_b32_e32 v1, v4
	v_lshl_add_u64 v[0:1], v[2:3], 0, v[0:1]
	v_cvt_pk_bf16_f32 v2, v6, v7
	v_cvt_pk_bf16_f32 v3, v8, v9
	s_waitcnt lgkmcnt(0)
	global_store_dwordx4 v185, v[186:189], s[70:71]
	global_store_dwordx4 v185, v[190:193], s[70:71] offset:2048
	s_nop 0
	v_readfirstlane_b32 s70, v0
	v_readfirstlane_b32 s71, v1
	ds_write_b64 v182, v[2:3]
	v_cvt_pk_bf16_f32 v2, v10, v11
	v_cvt_pk_bf16_f32 v3, v12, v13
	ds_write_b64 v182, v[2:3] offset:16
	v_cvt_pk_bf16_f32 v2, v14, v15
	v_cvt_pk_bf16_f32 v3, v16, v17
	ds_write_b64 v182, v[2:3] offset:32
	v_cvt_pk_bf16_f32 v2, v18, v19
	v_cvt_pk_bf16_f32 v3, v20, v21
	ds_write_b64 v182, v[2:3] offset:48
	ds_read_b128 v[186:189], v183
	ds_read_b128 v[190:193], v183 offset:1280
	s_waitcnt lgkmcnt(1)
	global_store_dwordx4 v185, v[186:189], s[70:71] offset:64
	s_waitcnt lgkmcnt(0)
	global_store_dwordx4 v185, v[190:193], s[70:71] offset:2112

.LBB0_972:
	s_or_b64 exec, exec, s[0:1]
	v_add_u32_e32 v154, v3, v139
	v_ashrrev_i32_e32 v155, 31, v154
	v_lshlrev_b64 v[2:3], v2, v[154:155]
	v_mov_b32_e32 v145, v4
	v_lshl_add_u64 v[146:147], s[26:27], 0, v[146:147]
	v_lshl_add_u64 v[2:3], v[2:3], 0, v[144:145]
	v_mad_u64_u32 v[144:145], s[0:1], v2, s50, v[146:147]
	v_mad_i32_i24 v145, v3, s50, v145
	v_ashrrev_i32_e32 v135, 31, v134
	v_lshl_add_u64 v[144:145], v[134:135], 1, v[144:145]
	v_lshlrev_b32_e32 v2, 1, v152
	v_mov_b32_e32 v3, v4
	v_pk_mul_f32 v[118:119], v[118:119], s[64:65] op_sel_hi:[1,0]
	v_pk_mul_f32 v[120:121], v[120:121], s[64:65] op_sel_hi:[1,0]
	v_lshl_add_u64 v[144:145], v[144:145], 0, v[2:3]
	v_cvt_pk_bf16_f32 v118, v118, v119
	v_cvt_pk_bf16_f32 v119, v120, v121
	s_nop 0
	v_readfirstlane_b32 s70, v144
	v_readfirstlane_b32 s71, v145
	ds_write_b64 v182, v[118:119]
	v_pk_mul_f32 v[118:119], v[122:123], s[64:65] op_sel_hi:[1,0]
	v_pk_mul_f32 v[120:121], v[124:125], s[64:65] op_sel_hi:[1,0]
	v_cvt_pk_bf16_f32 v118, v118, v119
	v_cvt_pk_bf16_f32 v119, v120, v121
	ds_write_b64 v182, v[118:119] offset:16
	v_pk_mul_f32 v[118:119], v[126:127], s[64:65] op_sel_hi:[1,0]
	v_pk_mul_f32 v[120:121], v[128:129], s[64:65] op_sel_hi:[1,0]
	v_cvt_pk_bf16_f32 v118, v118, v119
	v_cvt_pk_bf16_f32 v119, v120, v121
	ds_write_b64 v182, v[118:119] offset:32
	v_pk_mul_f32 v[118:119], v[130:131], s[64:65] op_sel_hi:[1,0]
	v_pk_mul_f32 v[120:121], v[132:133], s[64:65] op_sel_hi:[1,0]
	v_cvt_pk_bf16_f32 v118, v118, v119
	v_cvt_pk_bf16_f32 v119, v120, v121
	v_mov_b64_e32 v[122:123], 0xb152000
	v_mov_b64_e32 v[120:121], 8
	v_mov_b32_e32 v3, v148
	ds_write_b64 v182, v[118:119] offset:48
	ds_read_b128 v[186:189], v183
	ds_read_b128 v[190:193], v183 offset:1280
	s_and_saveexec_b64 s[0:1], s[6:7]
	v_mov_b64_e32 v[122:123], 0xbd52000
	v_mov_b64_e32 v[120:121], 12
	v_mov_b32_e32 v3, v150
	v_mov_b32_e32 v136, v137
	s_or_b64 exec, exec, s[0:1]
	v_or_b32_e32 v1, 32, v151
	s_mov_b32 s0, 0x2aaaaaab
	v_mul_hi_i32 v118, v1, s0
	v_lshrrev_b32_e32 v119, 31, v118
	v_ashrrev_i32_e32 v118, 4, v118
	v_add_u32_e32 v121, v118, v119
	s_movk_i32 s0, 0x60
	v_mul_lo_u32 v118, v121, s0
	v_sub_u32_e32 v118, v1, v118
	v_cmp_eq_u32_e64 s[4:5], 64, v118
	s_and_b64 s[6:7], s[6:7], s[4:5]
	s_and_saveexec_b64 s[0:1], s[6:7]
	s_cbranch_execz .LBB0_976
	v_readlane_b32 s6, v253, 31
	v_lshlrev_b32_e32 v124, 7, v136
	v_mov_b32_e32 v125, v4
	v_readlane_b32 s7, v253, 32
	v_mov_b32_e32 v1, v4
	s_nop 0
	v_lshl_add_u64 v[126:127], s[6:7], 0, v[124:125]
	v_readlane_b32 s6, v254, 47
	v_readlane_b32 s7, v254, 48
	v_lshl_add_u64 v[132:133], v[126:127], 0, v[0:1]
	s_nop 0
	v_lshl_add_u64 v[124:125], s[6:7], 0, v[124:125]
	v_lshl_add_u64 v[144:145], v[124:125], 0, v[0:1]
	global_load_dwordx4 v[124:127], v[132:133], off
	global_load_dwordx4 v[128:131], v[144:145], off
	s_waitcnt vmcnt(0)
	v_pk_mul_f32 v[146:147], v[106:107], v[128:129]
	s_nop 0
	v_pk_fma_f32 v[146:147], v[102:103], v[124:125], v[146:147] neg_lo:[0,0,1] neg_hi:[0,0,1]
	v_pk_mul_f32 v[102:103], v[102:103], v[128:129]
	s_nop 0
	v_pk_fma_f32 v[106:107], v[106:107], v[124:125], v[102:103]
	v_pk_mul_f32 v[102:103], v[108:109], v[130:131]
	s_nop 0
	v_pk_fma_f32 v[128:129], v[104:105], v[126:127], v[102:103] neg_lo:[0,0,1] neg_hi:[0,0,1]
	v_pk_mul_f32 v[102:103], v[104:105], v[130:131]
	s_nop 0
	v_pk_fma_f32 v[108:109], v[108:109], v[126:127], v[102:103]
	global_load_dwordx4 v[102:105], v[132:133], off offset:64
	global_load_dwordx4 v[124:127], v[144:145], off offset:64
	s_waitcnt vmcnt(0)
	v_pk_mul_f32 v[130:131], v[114:115], v[124:125]
	s_nop 0
	v_pk_fma_f32 v[130:131], v[110:111], v[102:103], v[130:131] neg_lo:[0,0,1] neg_hi:[0,0,1]
	v_pk_mul_f32 v[110:111], v[110:111], v[124:125]
	s_nop 0
	v_pk_fma_f32 v[114:115], v[114:115], v[102:103], v[110:111]
	v_pk_mul_f32 v[102:103], v[116:117], v[126:127]
	v_mov_b32_e32 v110, v130
	v_pk_fma_f32 v[124:125], v[112:113], v[104:105], v[102:103] neg_lo:[0,0,1] neg_hi:[0,0,1]
	v_pk_mul_f32 v[102:103], v[112:113], v[126:127]
	v_mov_b32_e32 v111, v131
	v_pk_fma_f32 v[116:117], v[116:117], v[104:105], v[102:103]
	v_mov_b32_e32 v102, v146
	v_mov_b32_e32 v103, v147
	v_mov_b32_e32 v104, v128
	v_mov_b32_e32 v105, v129
	v_mov_b32_e32 v112, v124
	v_mov_b32_e32 v113, v125
.LBB0_976:
	s_or_b64 exec, exec, s[0:1]
	v_add_u32_e32 v124, v3, v121
	v_ashrrev_i32_e32 v125, 31, v124
	v_lshlrev_b64 v[124:125], v120, v[124:125]
	v_mov_b32_e32 v137, v4
	v_lshl_add_u64 v[122:123], s[26:27], 0, v[122:123]
	v_lshl_add_u64 v[124:125], v[124:125], 0, v[136:137]
	v_mad_u64_u32 v[122:123], s[0:1], v124, s50, v[122:123]
	v_mad_i32_i24 v123, v125, s50, v123
	v_ashrrev_i32_e32 v119, 31, v118
	v_lshl_add_u64 v[122:123], v[118:119], 1, v[122:123]
	v_mov_b32_e32 v3, v4
	v_pk_mul_f32 v[102:103], v[102:103], s[64:65] op_sel_hi:[1,0]
	v_pk_mul_f32 v[104:105], v[104:105], s[64:65] op_sel_hi:[1,0]
	v_lshl_add_u64 v[122:123], v[122:123], 0, v[2:3]
	v_cvt_pk_bf16_f32 v102, v102, v103
	v_cvt_pk_bf16_f32 v103, v104, v105
	s_waitcnt lgkmcnt(0)
	global_store_dwordx4 v184, v[186:189], s[70:71]
	global_store_dwordx4 v184, v[190:193], s[70:71] offset:3072
	s_nop 0
	v_readfirstlane_b32 s70, v122
	v_readfirstlane_b32 s71, v123
	ds_write_b64 v182, v[102:103]
	v_pk_mul_f32 v[102:103], v[106:107], s[64:65] op_sel_hi:[1,0]
	v_pk_mul_f32 v[104:105], v[108:109], s[64:65] op_sel_hi:[1,0]
	v_cvt_pk_bf16_f32 v102, v102, v103
	v_cvt_pk_bf16_f32 v103, v104, v105
	ds_write_b64 v182, v[102:103] offset:16
	v_pk_mul_f32 v[102:103], v[110:111], s[64:65] op_sel_hi:[1,0]
	v_pk_mul_f32 v[104:105], v[112:113], s[64:65] op_sel_hi:[1,0]
	v_cvt_pk_bf16_f32 v102, v102, v103
	v_cvt_pk_bf16_f32 v103, v104, v105
	ds_write_b64 v182, v[102:103] offset:32
	v_pk_mul_f32 v[102:103], v[114:115], s[64:65] op_sel_hi:[1,0]
	v_pk_mul_f32 v[104:105], v[116:117], s[64:65] op_sel_hi:[1,0]
	v_or_b32_e32 v1, 32, v149
	v_cvt_pk_bf16_f32 v102, v102, v103
	v_cvt_pk_bf16_f32 v103, v104, v105
	v_cmp_lt_i32_e64 s[6:7], s89, v1
	s_movk_i32 s0, 0xbf
	v_add_u32_e32 v1, 0xffffe020, v149
	ds_write_b64 v182, v[102:103] offset:48
	ds_read_b128 v[186:189], v183
	ds_read_b128 v[190:193], v183 offset:1280
	v_bitop3_b32 v102, v149, s0, 32 bitop3:0xc8
	s_movk_i32 s0, 0xfbf
	v_lshrrev_b32_e32 v1, 9, v1
	v_bitop3_b32 v103, v149, s0, 32 bitop3:0xc8
	v_and_b32_e32 v110, 0x7ffff8, v1
	v_mov_b64_e32 v[108:109], 0xb152000
	v_mov_b64_e32 v[104:105], 8
	v_mov_b32_e32 v3, v148
	v_mov_b32_e32 v106, v102
	s_and_saveexec_b64 s[0:1], s[6:7]
	v_mov_b64_e32 v[108:109], 0xbd52000
	v_mov_b64_e32 v[104:105], 12
	v_mov_b32_e32 v3, v110
	v_mov_b32_e32 v106, v103
	s_or_b64 exec, exec, s[0:1]
	s_and_b64 s[14:15], s[6:7], vcc
	s_and_saveexec_b64 s[0:1], s[14:15]
	s_cbranch_execz .LBB0_980
	v_readlane_b32 s14, v253, 31
	v_lshlrev_b32_e32 v112, 7, v106
	v_mov_b32_e32 v113, v4
	v_readlane_b32 s15, v253, 32
	v_mov_b32_e32 v1, v4
	s_nop 0
	v_lshl_add_u64 v[114:115], s[14:15], 0, v[112:113]
	v_readlane_b32 s14, v254, 47
	v_readlane_b32 s15, v254, 48
	v_lshl_add_u64 v[116:117], v[114:115], 0, v[0:1]
	s_nop 0
	v_lshl_add_u64 v[112:113], s[14:15], 0, v[112:113]
	v_lshl_add_u64 v[126:127], v[112:113], 0, v[0:1]
	global_load_dwordx4 v[112:115], v[116:117], off
	global_load_dwordx4 v[122:125], v[126:127], off
	s_waitcnt vmcnt(0)
	v_pk_mul_f32 v[128:129], v[90:91], v[122:123]
	s_nop 0
	v_pk_fma_f32 v[128:129], v[86:87], v[112:113], v[128:129] neg_lo:[0,0,1] neg_hi:[0,0,1]
	v_pk_mul_f32 v[86:87], v[86:87], v[122:123]
	s_nop 0
	v_pk_fma_f32 v[90:91], v[90:91], v[112:113], v[86:87]
	v_pk_mul_f32 v[86:87], v[92:93], v[124:125]
	s_nop 0
	v_pk_fma_f32 v[122:123], v[88:89], v[114:115], v[86:87] neg_lo:[0,0,1] neg_hi:[0,0,1]
	v_pk_mul_f32 v[86:87], v[88:89], v[124:125]
	s_nop 0
	v_pk_fma_f32 v[92:93], v[92:93], v[114:115], v[86:87]
	global_load_dwordx4 v[86:89], v[116:117], off offset:64
	global_load_dwordx4 v[112:115], v[126:127], off offset:64
	s_waitcnt vmcnt(0)
	v_pk_mul_f32 v[116:117], v[98:99], v[112:113]
	s_nop 0
	v_pk_fma_f32 v[116:117], v[94:95], v[86:87], v[116:117] neg_lo:[0,0,1] neg_hi:[0,0,1]
	v_pk_mul_f32 v[94:95], v[94:95], v[112:113]
	s_nop 0
	v_pk_fma_f32 v[98:99], v[98:99], v[86:87], v[94:95]
	v_pk_mul_f32 v[86:87], v[100:101], v[114:115]
	v_mov_b32_e32 v94, v116
	v_pk_fma_f32 v[112:113], v[96:97], v[88:89], v[86:87] neg_lo:[0,0,1] neg_hi:[0,0,1]
	v_pk_mul_f32 v[86:87], v[96:97], v[114:115]
	v_mov_b32_e32 v95, v117
	v_pk_fma_f32 v[100:101], v[100:101], v[88:89], v[86:87]
	v_mov_b32_e32 v86, v128
	v_mov_b32_e32 v87, v129
	v_mov_b32_e32 v88, v122
	v_mov_b32_e32 v89, v123
	v_mov_b32_e32 v96, v112
	v_mov_b32_e32 v97, v113
.LBB0_980:
	s_or_b64 exec, exec, s[0:1]
	v_add_u32_e32 v112, v3, v139
	v_ashrrev_i32_e32 v113, 31, v112
	v_lshlrev_b64 v[104:105], v104, v[112:113]
	v_mov_b32_e32 v107, v4
	v_lshl_add_u64 v[108:109], s[26:27], 0, v[108:109]
	v_lshl_add_u64 v[104:105], v[104:105], 0, v[106:107]
	v_mad_u64_u32 v[106:107], s[0:1], v104, s50, v[108:109]
	v_mad_i32_i24 v107, v105, s50, v107
	v_lshl_add_u64 v[104:105], v[134:135], 1, v[106:107]
	v_mov_b32_e32 v3, v4
	v_pk_mul_f32 v[86:87], v[86:87], s[64:65] op_sel_hi:[1,0]
	v_pk_mul_f32 v[88:89], v[88:89], s[64:65] op_sel_hi:[1,0]
	v_lshl_add_u64 v[104:105], v[104:105], 0, v[2:3]
	v_cvt_pk_bf16_f32 v86, v86, v87
	v_cvt_pk_bf16_f32 v87, v88, v89
	s_waitcnt lgkmcnt(0)
	global_store_dwordx4 v184, v[186:189], s[70:71]
	global_store_dwordx4 v184, v[190:193], s[70:71] offset:3072
	s_nop 0
	v_readfirstlane_b32 s70, v104
	v_readfirstlane_b32 s71, v105
	ds_write_b64 v182, v[86:87]
	v_pk_mul_f32 v[86:87], v[90:91], s[64:65] op_sel_hi:[1,0]
	v_pk_mul_f32 v[88:89], v[92:93], s[64:65] op_sel_hi:[1,0]
	v_cvt_pk_bf16_f32 v86, v86, v87
	v_cvt_pk_bf16_f32 v87, v88, v89
	ds_write_b64 v182, v[86:87] offset:16
	v_pk_mul_f32 v[86:87], v[94:95], s[64:65] op_sel_hi:[1,0]
	v_pk_mul_f32 v[88:89], v[96:97], s[64:65] op_sel_hi:[1,0]
	v_cvt_pk_bf16_f32 v86, v86, v87
	v_cvt_pk_bf16_f32 v87, v88, v89
	ds_write_b64 v182, v[86:87] offset:32
	v_pk_mul_f32 v[86:87], v[98:99], s[64:65] op_sel_hi:[1,0]
	v_pk_mul_f32 v[88:89], v[100:101], s[64:65] op_sel_hi:[1,0]
	v_cvt_pk_bf16_f32 v86, v86, v87
	v_cvt_pk_bf16_f32 v87, v88, v89
	ds_write_b64 v182, v[86:87] offset:48
	ds_read_b128 v[186:189], v183
	ds_read_b128 v[190:193], v183 offset:1280
	v_mov_b64_e32 v[88:89], 0xb152000
	v_mov_b64_e32 v[86:87], 8
	v_mov_b32_e32 v3, v148
	s_and_saveexec_b64 s[0:1], s[6:7]
	v_mov_b64_e32 v[88:89], 0xbd52000
	v_mov_b64_e32 v[86:87], 12
	v_mov_b32_e32 v3, v110
	v_mov_b32_e32 v102, v103
	s_or_b64 exec, exec, s[0:1]
	s_and_b64 s[6:7], s[6:7], s[4:5]
	s_and_saveexec_b64 s[0:1], s[6:7]
	s_cbranch_execz .LBB0_984
	v_readlane_b32 s6, v253, 31
	v_lshlrev_b32_e32 v90, 7, v102
	v_mov_b32_e32 v91, v4
	v_readlane_b32 s7, v253, 32
	v_mov_b32_e32 v1, v4
	s_nop 0
	v_lshl_add_u64 v[92:93], s[6:7], 0, v[90:91]
	v_readlane_b32 s6, v254, 47
	v_readlane_b32 s7, v254, 48
	v_lshl_add_u64 v[98:99], v[92:93], 0, v[0:1]
	s_nop 0
	v_lshl_add_u64 v[90:91], s[6:7], 0, v[90:91]
	v_lshl_add_u64 v[100:101], v[90:91], 0, v[0:1]
	global_load_dwordx4 v[90:93], v[98:99], off
	global_load_dwordx4 v[94:97], v[100:101], off
	s_waitcnt vmcnt(0)
	v_pk_mul_f32 v[104:105], v[74:75], v[94:95]
	s_nop 0
	v_pk_fma_f32 v[104:105], v[70:71], v[90:91], v[104:105] neg_lo:[0,0,1] neg_hi:[0,0,1]
	v_pk_mul_f32 v[70:71], v[70:71], v[94:95]
	s_nop 0
	v_pk_fma_f32 v[74:75], v[74:75], v[90:91], v[70:71]
	v_pk_mul_f32 v[70:71], v[76:77], v[96:97]
	s_nop 0
	v_pk_fma_f32 v[94:95], v[72:73], v[92:93], v[70:71] neg_lo:[0,0,1] neg_hi:[0,0,1]
	v_pk_mul_f32 v[70:71], v[72:73], v[96:97]
	s_nop 0
	v_pk_fma_f32 v[76:77], v[76:77], v[92:93], v[70:71]
	global_load_dwordx4 v[70:73], v[98:99], off offset:64
	global_load_dwordx4 v[90:93], v[100:101], off offset:64
	s_waitcnt vmcnt(0)
	v_pk_mul_f32 v[96:97], v[82:83], v[90:91]
	s_nop 0
	v_pk_fma_f32 v[96:97], v[78:79], v[70:71], v[96:97] neg_lo:[0,0,1] neg_hi:[0,0,1]
	v_pk_mul_f32 v[78:79], v[78:79], v[90:91]
	s_nop 0
	v_pk_fma_f32 v[82:83], v[82:83], v[70:71], v[78:79]
	v_pk_mul_f32 v[70:71], v[84:85], v[92:93]
	v_mov_b32_e32 v78, v96
	v_pk_fma_f32 v[90:91], v[80:81], v[72:73], v[70:71] neg_lo:[0,0,1] neg_hi:[0,0,1]
	v_pk_mul_f32 v[70:71], v[80:81], v[92:93]
	v_mov_b32_e32 v79, v97
	v_pk_fma_f32 v[84:85], v[84:85], v[72:73], v[70:71]
	v_mov_b32_e32 v70, v104
	v_mov_b32_e32 v71, v105
	v_mov_b32_e32 v72, v94
	v_mov_b32_e32 v73, v95
	v_mov_b32_e32 v80, v90
	v_mov_b32_e32 v81, v91
.LBB0_984:
	s_or_b64 exec, exec, s[0:1]
	v_add_u32_e32 v90, v3, v121
	v_ashrrev_i32_e32 v91, 31, v90
	v_lshlrev_b64 v[86:87], v86, v[90:91]
	v_mov_b32_e32 v103, v4
	v_lshl_add_u64 v[88:89], s[26:27], 0, v[88:89]
	v_lshl_add_u64 v[86:87], v[86:87], 0, v[102:103]
	v_mad_u64_u32 v[88:89], s[0:1], v86, s50, v[88:89]
	v_mad_i32_i24 v89, v87, s50, v89
	v_lshl_add_u64 v[86:87], v[118:119], 1, v[88:89]
	v_mov_b32_e32 v3, v4
	v_pk_mul_f32 v[70:71], v[70:71], s[64:65] op_sel_hi:[1,0]
	v_pk_mul_f32 v[72:73], v[72:73], s[64:65] op_sel_hi:[1,0]
	v_lshl_add_u64 v[86:87], v[86:87], 0, v[2:3]
	v_cvt_pk_bf16_f32 v70, v70, v71
	v_cvt_pk_bf16_f32 v71, v72, v73
	s_waitcnt lgkmcnt(0)
	global_store_dwordx4 v184, v[186:189], s[70:71]
	global_store_dwordx4 v184, v[190:193], s[70:71] offset:3072
	s_nop 0
	v_readfirstlane_b32 s70, v86
	v_readfirstlane_b32 s71, v87
	ds_write_b64 v182, v[70:71]
	v_pk_mul_f32 v[70:71], v[74:75], s[64:65] op_sel_hi:[1,0]
	v_pk_mul_f32 v[72:73], v[76:77], s[64:65] op_sel_hi:[1,0]
	v_cvt_pk_bf16_f32 v70, v70, v71
	v_cvt_pk_bf16_f32 v71, v72, v73
	ds_write_b64 v182, v[70:71] offset:16
	v_pk_mul_f32 v[70:71], v[78:79], s[64:65] op_sel_hi:[1,0]
	v_pk_mul_f32 v[72:73], v[80:81], s[64:65] op_sel_hi:[1,0]
	v_cvt_pk_bf16_f32 v70, v70, v71
	v_cvt_pk_bf16_f32 v71, v72, v73
	ds_write_b64 v182, v[70:71] offset:32
	v_pk_mul_f32 v[70:71], v[82:83], s[64:65] op_sel_hi:[1,0]
	v_pk_mul_f32 v[72:73], v[84:85], s[64:65] op_sel_hi:[1,0]
	v_or_b32_e32 v1, 64, v149
	v_cvt_pk_bf16_f32 v70, v70, v71
	v_cvt_pk_bf16_f32 v71, v72, v73
	v_cmp_lt_i32_e64 s[6:7], s89, v1
	s_movk_i32 s0, 0xdf
	v_add_u32_e32 v1, 0xffffe040, v149
	ds_write_b64 v182, v[70:71] offset:48
	ds_read_b128 v[186:189], v183
	ds_read_b128 v[190:193], v183 offset:1280
	v_bitop3_b32 v70, v149, s0, 64 bitop3:0xc8
	s_movk_i32 s0, 0xfdf
	v_lshrrev_b32_e32 v1, 9, v1
	v_bitop3_b32 v71, v149, s0, 64 bitop3:0xc8
	v_and_b32_e32 v78, 0x7ffff8, v1
	v_mov_b64_e32 v[76:77], 0xb152000
	v_mov_b64_e32 v[72:73], 8
	v_mov_b32_e32 v3, v148
	v_mov_b32_e32 v74, v70
	s_and_saveexec_b64 s[0:1], s[6:7]
	v_mov_b64_e32 v[76:77], 0xbd52000
	v_mov_b64_e32 v[72:73], 12
	v_mov_b32_e32 v3, v78
	v_mov_b32_e32 v74, v71
	s_or_b64 exec, exec, s[0:1]
	s_and_b64 s[14:15], s[6:7], vcc
	s_and_saveexec_b64 s[0:1], s[14:15]
	s_cbranch_execz .LBB0_988
	v_readlane_b32 s14, v253, 31
	v_lshlrev_b32_e32 v80, 7, v74
	v_mov_b32_e32 v81, v4
	v_readlane_b32 s15, v253, 32
	v_mov_b32_e32 v1, v4
	s_nop 0
	v_lshl_add_u64 v[82:83], s[14:15], 0, v[80:81]
	v_readlane_b32 s14, v254, 47
	v_readlane_b32 s15, v254, 48
	v_lshl_add_u64 v[88:89], v[82:83], 0, v[0:1]
	s_nop 0
	v_lshl_add_u64 v[80:81], s[14:15], 0, v[80:81]
	v_lshl_add_u64 v[90:91], v[80:81], 0, v[0:1]
	global_load_dwordx4 v[80:83], v[88:89], off
	global_load_dwordx4 v[84:87], v[90:91], off
	s_waitcnt vmcnt(0)
	v_pk_mul_f32 v[92:93], v[58:59], v[84:85]
	s_nop 0
	v_pk_fma_f32 v[92:93], v[54:55], v[80:81], v[92:93] neg_lo:[0,0,1] neg_hi:[0,0,1]
	v_pk_mul_f32 v[54:55], v[54:55], v[84:85]
	s_nop 0
	v_pk_fma_f32 v[58:59], v[58:59], v[80:81], v[54:55]
	v_pk_mul_f32 v[54:55], v[60:61], v[86:87]
	s_nop 0
	v_pk_fma_f32 v[84:85], v[56:57], v[82:83], v[54:55] neg_lo:[0,0,1] neg_hi:[0,0,1]
	v_pk_mul_f32 v[54:55], v[56:57], v[86:87]
	s_nop 0
	v_pk_fma_f32 v[60:61], v[60:61], v[82:83], v[54:55]
	global_load_dwordx4 v[54:57], v[88:89], off offset:64
	global_load_dwordx4 v[80:83], v[90:91], off offset:64
	s_waitcnt vmcnt(0)
	v_pk_mul_f32 v[86:87], v[66:67], v[80:81]
	s_nop 0
	v_pk_fma_f32 v[86:87], v[62:63], v[54:55], v[86:87] neg_lo:[0,0,1] neg_hi:[0,0,1]
	v_pk_mul_f32 v[62:63], v[62:63], v[80:81]
	s_nop 0
	v_pk_fma_f32 v[66:67], v[66:67], v[54:55], v[62:63]
	v_pk_mul_f32 v[54:55], v[68:69], v[82:83]
	v_mov_b32_e32 v62, v86
	v_pk_fma_f32 v[80:81], v[64:65], v[56:57], v[54:55] neg_lo:[0,0,1] neg_hi:[0,0,1]
	v_pk_mul_f32 v[54:55], v[64:65], v[82:83]
	v_mov_b32_e32 v63, v87
	v_pk_fma_f32 v[68:69], v[68:69], v[56:57], v[54:55]
	v_mov_b32_e32 v54, v92
	v_mov_b32_e32 v55, v93
	v_mov_b32_e32 v56, v84
	v_mov_b32_e32 v57, v85
	v_mov_b32_e32 v64, v80
	v_mov_b32_e32 v65, v81
.LBB0_988:
	s_or_b64 exec, exec, s[0:1]
	v_add_u32_e32 v80, v3, v139
	v_ashrrev_i32_e32 v81, 31, v80
	v_lshlrev_b64 v[72:73], v72, v[80:81]
	v_mov_b32_e32 v75, v4
	v_lshl_add_u64 v[76:77], s[26:27], 0, v[76:77]
	v_lshl_add_u64 v[72:73], v[72:73], 0, v[74:75]
	v_mad_u64_u32 v[74:75], s[0:1], v72, s50, v[76:77]
	v_mad_i32_i24 v75, v73, s50, v75
	v_lshl_add_u64 v[72:73], v[134:135], 1, v[74:75]
	v_mov_b32_e32 v3, v4
	v_pk_mul_f32 v[54:55], v[54:55], s[64:65] op_sel_hi:[1,0]
	v_pk_mul_f32 v[56:57], v[56:57], s[64:65] op_sel_hi:[1,0]
	v_lshl_add_u64 v[72:73], v[72:73], 0, v[2:3]
	v_cvt_pk_bf16_f32 v54, v54, v55
	v_cvt_pk_bf16_f32 v55, v56, v57
	s_waitcnt lgkmcnt(0)
	global_store_dwordx4 v184, v[186:189], s[70:71]
	global_store_dwordx4 v184, v[190:193], s[70:71] offset:3072
	s_nop 0
	v_readfirstlane_b32 s70, v72
	v_readfirstlane_b32 s71, v73
	ds_write_b64 v182, v[54:55]
	v_pk_mul_f32 v[54:55], v[58:59], s[64:65] op_sel_hi:[1,0]
	v_pk_mul_f32 v[56:57], v[60:61], s[64:65] op_sel_hi:[1,0]
	v_cvt_pk_bf16_f32 v54, v54, v55
	v_cvt_pk_bf16_f32 v55, v56, v57
	ds_write_b64 v182, v[54:55] offset:16
	v_pk_mul_f32 v[54:55], v[62:63], s[64:65] op_sel_hi:[1,0]
	v_pk_mul_f32 v[56:57], v[64:65], s[64:65] op_sel_hi:[1,0]
	v_cvt_pk_bf16_f32 v54, v54, v55
	v_cvt_pk_bf16_f32 v55, v56, v57
	ds_write_b64 v182, v[54:55] offset:32
	v_pk_mul_f32 v[54:55], v[66:67], s[64:65] op_sel_hi:[1,0]
	v_pk_mul_f32 v[56:57], v[68:69], s[64:65] op_sel_hi:[1,0]
	v_cvt_pk_bf16_f32 v54, v54, v55
	v_cvt_pk_bf16_f32 v55, v56, v57
	ds_write_b64 v182, v[54:55] offset:48
	ds_read_b128 v[186:189], v183
	ds_read_b128 v[190:193], v183 offset:1280
	v_mov_b64_e32 v[56:57], 0xb152000
	v_mov_b64_e32 v[54:55], 8
	v_mov_b32_e32 v3, v148
	s_and_saveexec_b64 s[0:1], s[6:7]
	v_mov_b64_e32 v[56:57], 0xbd52000
	v_mov_b64_e32 v[54:55], 12
	v_mov_b32_e32 v3, v78
	v_mov_b32_e32 v70, v71
	s_or_b64 exec, exec, s[0:1]
	s_and_b64 s[6:7], s[6:7], s[4:5]
	s_and_saveexec_b64 s[0:1], s[6:7]
	s_cbranch_execz .LBB0_992
	v_readlane_b32 s6, v253, 31
	v_lshlrev_b32_e32 v58, 7, v70
	v_mov_b32_e32 v59, v4
	v_readlane_b32 s7, v253, 32
	v_mov_b32_e32 v1, v4
	s_nop 0
	v_lshl_add_u64 v[60:61], s[6:7], 0, v[58:59]
	v_readlane_b32 s6, v254, 47
	v_readlane_b32 s7, v254, 48
	v_lshl_add_u64 v[66:67], v[60:61], 0, v[0:1]
	s_nop 0
	v_lshl_add_u64 v[58:59], s[6:7], 0, v[58:59]
	v_lshl_add_u64 v[68:69], v[58:59], 0, v[0:1]
	global_load_dwordx4 v[58:61], v[66:67], off
	global_load_dwordx4 v[62:65], v[68:69], off
	s_waitcnt vmcnt(0)
	v_pk_mul_f32 v[72:73], v[42:43], v[62:63]
	s_nop 0
	v_pk_fma_f32 v[72:73], v[38:39], v[58:59], v[72:73] neg_lo:[0,0,1] neg_hi:[0,0,1]
	v_pk_mul_f32 v[38:39], v[38:39], v[62:63]
	s_nop 0
	v_pk_fma_f32 v[42:43], v[42:43], v[58:59], v[38:39]
	v_pk_mul_f32 v[38:39], v[44:45], v[64:65]
	s_nop 0
	v_pk_fma_f32 v[62:63], v[40:41], v[60:61], v[38:39] neg_lo:[0,0,1] neg_hi:[0,0,1]
	v_pk_mul_f32 v[38:39], v[40:41], v[64:65]
	s_nop 0
	v_pk_fma_f32 v[44:45], v[44:45], v[60:61], v[38:39]
	global_load_dwordx4 v[38:41], v[66:67], off offset:64
	global_load_dwordx4 v[58:61], v[68:69], off offset:64
	s_waitcnt vmcnt(0)
	v_pk_mul_f32 v[64:65], v[50:51], v[58:59]
	s_nop 0
	v_pk_fma_f32 v[64:65], v[46:47], v[38:39], v[64:65] neg_lo:[0,0,1] neg_hi:[0,0,1]
	v_pk_mul_f32 v[46:47], v[46:47], v[58:59]
	s_nop 0
	v_pk_fma_f32 v[50:51], v[50:51], v[38:39], v[46:47]
	v_pk_mul_f32 v[38:39], v[52:53], v[60:61]
	v_mov_b32_e32 v46, v64
	v_pk_fma_f32 v[58:59], v[48:49], v[40:41], v[38:39] neg_lo:[0,0,1] neg_hi:[0,0,1]
	v_pk_mul_f32 v[38:39], v[48:49], v[60:61]
	v_mov_b32_e32 v47, v65
	v_pk_fma_f32 v[52:53], v[52:53], v[40:41], v[38:39]
	v_mov_b32_e32 v38, v72
	v_mov_b32_e32 v39, v73
	v_mov_b32_e32 v40, v62
	v_mov_b32_e32 v41, v63
	v_mov_b32_e32 v48, v58
	v_mov_b32_e32 v49, v59
.LBB0_992:
	s_or_b64 exec, exec, s[0:1]
	v_add_u32_e32 v58, v3, v121
	v_ashrrev_i32_e32 v59, 31, v58
	v_lshlrev_b64 v[54:55], v54, v[58:59]
	v_mov_b32_e32 v71, v4
	v_lshl_add_u64 v[56:57], s[26:27], 0, v[56:57]
	v_lshl_add_u64 v[54:55], v[54:55], 0, v[70:71]
	v_mad_u64_u32 v[56:57], s[0:1], v54, s50, v[56:57]
	v_mad_i32_i24 v57, v55, s50, v57
	v_lshl_add_u64 v[54:55], v[118:119], 1, v[56:57]
	v_mov_b32_e32 v3, v4
	v_pk_mul_f32 v[38:39], v[38:39], s[64:65] op_sel_hi:[1,0]
	v_pk_mul_f32 v[40:41], v[40:41], s[64:65] op_sel_hi:[1,0]
	v_lshl_add_u64 v[54:55], v[54:55], 0, v[2:3]
	v_cvt_pk_bf16_f32 v38, v38, v39
	v_cvt_pk_bf16_f32 v39, v40, v41
	s_waitcnt lgkmcnt(0)
	global_store_dwordx4 v184, v[186:189], s[70:71]
	global_store_dwordx4 v184, v[190:193], s[70:71] offset:3072
	s_nop 0
	v_readfirstlane_b32 s70, v54
	v_readfirstlane_b32 s71, v55
	ds_write_b64 v182, v[38:39]
	v_pk_mul_f32 v[38:39], v[42:43], s[64:65] op_sel_hi:[1,0]
	v_pk_mul_f32 v[40:41], v[44:45], s[64:65] op_sel_hi:[1,0]
	v_cvt_pk_bf16_f32 v38, v38, v39
	v_cvt_pk_bf16_f32 v39, v40, v41
	ds_write_b64 v182, v[38:39] offset:16
	v_pk_mul_f32 v[38:39], v[46:47], s[64:65] op_sel_hi:[1,0]
	v_pk_mul_f32 v[40:41], v[48:49], s[64:65] op_sel_hi:[1,0]
	v_cvt_pk_bf16_f32 v38, v38, v39
	v_cvt_pk_bf16_f32 v39, v40, v41
	ds_write_b64 v182, v[38:39] offset:32
	v_pk_mul_f32 v[38:39], v[50:51], s[64:65] op_sel_hi:[1,0]
	v_pk_mul_f32 v[40:41], v[52:53], s[64:65] op_sel_hi:[1,0]
	v_or_b32_e32 v1, 0x60, v149
	v_cvt_pk_bf16_f32 v38, v38, v39
	v_cvt_pk_bf16_f32 v39, v40, v41
	v_cmp_lt_i32_e64 s[6:7], s89, v1
	s_movk_i32 s0, 0xff
	v_add_u32_e32 v1, 0xffffe060, v149
	ds_write_b64 v182, v[38:39] offset:48
	ds_read_b128 v[186:189], v183
	ds_read_b128 v[190:193], v183 offset:1280
	v_bitop3_b32 v38, v149, s0, v251 bitop3:0xc8
	s_movk_i32 s0, 0xfff
	v_lshrrev_b32_e32 v1, 9, v1
	v_bitop3_b32 v39, v149, s0, v251 bitop3:0xc8
	v_and_b32_e32 v46, 0x7ffff8, v1
	v_mov_b64_e32 v[44:45], 0xb152000
	v_mov_b64_e32 v[40:41], 8
	v_mov_b32_e32 v3, v148
	v_mov_b32_e32 v42, v38
	s_and_saveexec_b64 s[0:1], s[6:7]
	v_mov_b64_e32 v[44:45], 0xbd52000
	v_mov_b64_e32 v[40:41], 12
	v_mov_b32_e32 v3, v46
	v_mov_b32_e32 v42, v39
	s_or_b64 exec, exec, s[0:1]
	s_and_b64 s[14:15], s[6:7], vcc
	s_and_saveexec_b64 s[0:1], s[14:15]
	s_cbranch_execz .LBB0_996
	v_readlane_b32 s14, v253, 31
	v_lshlrev_b32_e32 v48, 7, v42
	v_mov_b32_e32 v49, v4
	v_readlane_b32 s15, v253, 32
	v_mov_b32_e32 v1, v4
	s_nop 0
	v_lshl_add_u64 v[50:51], s[14:15], 0, v[48:49]
	v_readlane_b32 s14, v254, 47
	v_readlane_b32 s15, v254, 48
	v_lshl_add_u64 v[56:57], v[50:51], 0, v[0:1]
	s_nop 0
	v_lshl_add_u64 v[48:49], s[14:15], 0, v[48:49]
	v_lshl_add_u64 v[58:59], v[48:49], 0, v[0:1]
	global_load_dwordx4 v[48:51], v[56:57], off
	global_load_dwordx4 v[52:55], v[58:59], off
	s_waitcnt vmcnt(0)
	v_pk_mul_f32 v[60:61], v[26:27], v[52:53]
	s_nop 0
	v_pk_fma_f32 v[60:61], v[22:23], v[48:49], v[60:61] neg_lo:[0,0,1] neg_hi:[0,0,1]
	v_pk_mul_f32 v[22:23], v[22:23], v[52:53]
	s_nop 0
	v_pk_fma_f32 v[26:27], v[26:27], v[48:49], v[22:23]
	v_pk_mul_f32 v[22:23], v[28:29], v[54:55]
	s_nop 0
	v_pk_fma_f32 v[52:53], v[24:25], v[50:51], v[22:23] neg_lo:[0,0,1] neg_hi:[0,0,1]
	v_pk_mul_f32 v[22:23], v[24:25], v[54:55]
	s_nop 0
	v_pk_fma_f32 v[28:29], v[28:29], v[50:51], v[22:23]
	global_load_dwordx4 v[22:25], v[56:57], off offset:64
	global_load_dwordx4 v[48:51], v[58:59], off offset:64
	s_waitcnt vmcnt(0)
	v_pk_mul_f32 v[54:55], v[34:35], v[48:49]
	s_nop 0
	v_pk_fma_f32 v[54:55], v[30:31], v[22:23], v[54:55] neg_lo:[0,0,1] neg_hi:[0,0,1]
	v_pk_mul_f32 v[30:31], v[30:31], v[48:49]
	s_nop 0
	v_pk_fma_f32 v[34:35], v[34:35], v[22:23], v[30:31]
	v_pk_mul_f32 v[22:23], v[36:37], v[50:51]
	v_mov_b32_e32 v30, v54
	v_pk_fma_f32 v[48:49], v[32:33], v[24:25], v[22:23] neg_lo:[0,0,1] neg_hi:[0,0,1]
	v_pk_mul_f32 v[22:23], v[32:33], v[50:51]
	v_mov_b32_e32 v31, v55
	v_pk_fma_f32 v[36:37], v[36:37], v[24:25], v[22:23]
	v_mov_b32_e32 v22, v60
	v_mov_b32_e32 v23, v61
	v_mov_b32_e32 v24, v52
	v_mov_b32_e32 v25, v53
	v_mov_b32_e32 v32, v48
	v_mov_b32_e32 v33, v49
.LBB0_996:
	s_or_b64 exec, exec, s[0:1]
	v_add_u32_e32 v48, v3, v139
	v_ashrrev_i32_e32 v49, 31, v48
	v_lshlrev_b64 v[40:41], v40, v[48:49]
	v_mov_b32_e32 v43, v4
	v_lshl_add_u64 v[44:45], s[26:27], 0, v[44:45]
	v_lshl_add_u64 v[40:41], v[40:41], 0, v[42:43]
	v_mad_u64_u32 v[42:43], s[0:1], v40, s50, v[44:45]
	v_mad_i32_i24 v43, v41, s50, v43
	v_lshl_add_u64 v[40:41], v[134:135], 1, v[42:43]
	v_mov_b32_e32 v3, v4
	v_pk_mul_f32 v[22:23], v[22:23], s[64:65] op_sel_hi:[1,0]
	v_pk_mul_f32 v[24:25], v[24:25], s[64:65] op_sel_hi:[1,0]
	v_lshl_add_u64 v[40:41], v[40:41], 0, v[2:3]
	v_cvt_pk_bf16_f32 v22, v22, v23
	v_cvt_pk_bf16_f32 v23, v24, v25
	s_waitcnt lgkmcnt(0)
	global_store_dwordx4 v184, v[186:189], s[70:71]
	global_store_dwordx4 v184, v[190:193], s[70:71] offset:3072
	s_nop 0
	v_readfirstlane_b32 s70, v40
	v_readfirstlane_b32 s71, v41
	ds_write_b64 v182, v[22:23]
	v_pk_mul_f32 v[22:23], v[26:27], s[64:65] op_sel_hi:[1,0]
	v_pk_mul_f32 v[24:25], v[28:29], s[64:65] op_sel_hi:[1,0]
	v_cvt_pk_bf16_f32 v22, v22, v23
	v_cvt_pk_bf16_f32 v23, v24, v25
	ds_write_b64 v182, v[22:23] offset:16
	v_pk_mul_f32 v[22:23], v[30:31], s[64:65] op_sel_hi:[1,0]
	v_pk_mul_f32 v[24:25], v[32:33], s[64:65] op_sel_hi:[1,0]
	v_cvt_pk_bf16_f32 v22, v22, v23
	v_cvt_pk_bf16_f32 v23, v24, v25
	ds_write_b64 v182, v[22:23] offset:32
	v_pk_mul_f32 v[22:23], v[34:35], s[64:65] op_sel_hi:[1,0]
	v_pk_mul_f32 v[24:25], v[36:37], s[64:65] op_sel_hi:[1,0]
	v_cvt_pk_bf16_f32 v22, v22, v23
	v_cvt_pk_bf16_f32 v23, v24, v25
	ds_write_b64 v182, v[22:23] offset:48
	ds_read_b128 v[186:189], v183
	ds_read_b128 v[190:193], v183 offset:1280
	v_mov_b64_e32 v[24:25], 0xb152000
	v_mov_b64_e32 v[22:23], 8
	s_and_saveexec_b64 s[0:1], s[6:7]
	v_mov_b64_e32 v[24:25], 0xbd52000
	v_mov_b64_e32 v[22:23], 12
	v_mov_b32_e32 v148, v46
	v_mov_b32_e32 v38, v39
	s_or_b64 exec, exec, s[0:1]
	s_and_b64 s[4:5], s[6:7], s[4:5]
	s_and_saveexec_b64 s[0:1], s[4:5]
	s_cbranch_execz .LBB0_915
	v_readlane_b32 s4, v253, 31
	v_lshlrev_b32_e32 v26, 7, v38
	v_mov_b32_e32 v27, v4
	v_readlane_b32 s5, v253, 32
	v_mov_b32_e32 v1, v4
	s_nop 0
	v_lshl_add_u64 v[28:29], s[4:5], 0, v[26:27]
	v_readlane_b32 s4, v254, 47
	v_readlane_b32 s5, v254, 48
	v_lshl_add_u64 v[34:35], v[28:29], 0, v[0:1]
	s_nop 0
	v_lshl_add_u64 v[26:27], s[4:5], 0, v[26:27]
	v_lshl_add_u64 v[0:1], v[26:27], 0, v[0:1]
	global_load_dwordx4 v[26:29], v[34:35], off
	global_load_dwordx4 v[30:33], v[0:1], off
	s_waitcnt vmcnt(0)
	v_pk_mul_f32 v[36:37], v[10:11], v[30:31]
	s_nop 0
	v_pk_fma_f32 v[36:37], v[6:7], v[26:27], v[36:37] neg_lo:[0,0,1] neg_hi:[0,0,1]
	v_pk_mul_f32 v[6:7], v[6:7], v[30:31]
	s_nop 0
	v_pk_fma_f32 v[10:11], v[10:11], v[26:27], v[6:7]
	v_pk_mul_f32 v[6:7], v[12:13], v[32:33]
	s_nop 0
	v_pk_fma_f32 v[30:31], v[8:9], v[28:29], v[6:7] neg_lo:[0,0,1] neg_hi:[0,0,1]
	v_pk_mul_f32 v[6:7], v[8:9], v[32:33]
	s_nop 0
	v_pk_fma_f32 v[12:13], v[12:13], v[28:29], v[6:7]
	global_load_dwordx4 v[6:9], v[34:35], off offset:64
	global_load_dwordx4 v[26:29], v[0:1], off offset:64
	s_waitcnt vmcnt(0)
	v_pk_mul_f32 v[0:1], v[18:19], v[26:27]
	s_nop 0
	v_pk_fma_f32 v[0:1], v[14:15], v[6:7], v[0:1] neg_lo:[0,0,1] neg_hi:[0,0,1]
	v_pk_mul_f32 v[14:15], v[14:15], v[26:27]
	s_nop 0
	v_pk_fma_f32 v[18:19], v[18:19], v[6:7], v[14:15]
	v_pk_mul_f32 v[6:7], v[20:21], v[28:29]
	v_mov_b32_e32 v14, v0
	v_pk_fma_f32 v[26:27], v[16:17], v[8:9], v[6:7] neg_lo:[0,0,1] neg_hi:[0,0,1]
	v_pk_mul_f32 v[6:7], v[16:17], v[28:29]
	v_mov_b32_e32 v15, v1
	v_pk_fma_f32 v[20:21], v[20:21], v[8:9], v[6:7]
	v_mov_b32_e32 v6, v36
	v_mov_b32_e32 v7, v37
	v_mov_b32_e32 v8, v30
	v_mov_b32_e32 v9, v31
	v_mov_b32_e32 v16, v26
	v_mov_b32_e32 v17, v27
	s_branch .LBB0_915
